# work fetch: id broadcast through two alternating LDS words, second workgroup barrier of every fetch removed
# speedup vs baseline: 1.0145x; 1.0058x over previous
; #define LAS __attribute__((address_space(3)))
; DI int get_tid() { int t = threadIdx.x; asm volatile("" : "+v"(t)); return t; }
; DI void diff_item(const Params& P, char* lds, int layer, int pair, int qt, int& tab_head) {
;     ...
;         const float lam_init = 0.8f - 0.6f * expf(-0.3f * (float)layer);
; DI void phase_att(const Params& P, char* lds, int hb, int layer) {
;     unsigned* ctr = (unsigned*)(P.ws + WS_CTR) + (hb * 2 + layer) * 8;
;     LAS int* slot = (LAS int*)(lds + LDS_SLOT);
;     const int tid = get_tid();
;     constexpr int NQ = 64 + 384;
;     int tab_head = -1;
;     for (int dq = 0; dq < 8; ++dq) {
;         const int qx = (blockIdx.x + dq) & 7;
.LBB0_194:
	s_or_b64 exec, exec, s[0:1]
	v_writelane_b32 v236, s72, 46
	s_xor_b64 s[0:1], s[72:73], -1
	s_mov_b64 s[2:3], s[24:25]
	v_writelane_b32 v236, s73, 47
	v_readlane_b32 s20, v237, 12
	v_writelane_b32 v236, s0, 48
	v_readlane_b32 s21, v237, 13
	s_mov_b64 s[10:11], s[38:39]
	v_writelane_b32 v236, s1, 49
	s_mov_b64 s[4:5], s[98:99]
	s_mov_b64 s[6:7], s[28:29]
	s_mov_b64 s[30:31], s[20:21]
	s_mov_b64 s[0:1], s[60:61]
	v_mov_b32_e32 v0, v174
	s_waitcnt lgkmcnt(0)
	s_barrier
	s_lshl_b32 s2, s96, 3
	v_cmp_eq_u32_e64 s[36:37], 0, v0
	v_cvt_f32_u32_e32 v0, s96
	v_readlane_b32 s3, v236, 42
	s_or_b32 s16, s2, s3
	s_lshl_b64 s[2:3], s[16:17], 2
	v_mul_f32_e32 v0, 0xbe99999a, v0
	s_add_u32 s98, s0, s2
	v_mul_f32_e32 v2, 0x3fb8aa3b, v0
	s_mov_b32 s2, 0x3fb8aa3b
	v_fma_f32 v3, v0, s2, -v2
	v_rndne_f32_e32 v4, v2
	v_fmac_f32_e32 v3, 0x32a5705f, v0
	v_sub_f32_e32 v2, v2, v4
	s_addc_u32 s99, s1, s3
	v_add_f32_e32 v2, v2, v3
	s_lshl_b32 s16, s96, 7
	v_exp_f32_e32 v2, v2
	v_cvt_i32_f32_e32 v3, v4
	s_add_u32 s34, s0, 0xcf40000
	s_addc_u32 s35, s1, 0
	s_add_u32 s4, s0, 0xcd00000
	s_mov_b32 s2, 0xc2ce8ed0
	s_addc_u32 s5, s1, 0
	v_ldexp_f32 v2, v2, v3
	v_cmp_ngt_f32_e32 vcc, s2, v0
	s_mov_b32 s2, 0x42b17218
	s_add_u32 s6, s0, 0x8500000
	v_cndmask_b32_e32 v2, 0, v2, vcc
	v_cmp_nlt_f32_e32 vcc, s2, v0
	s_addc_u32 s7, s1, 0
	s_mov_b32 s2, s96
	s_mov_b32 s97, s17
	s_add_u32 s46, s0, 0x32000
	v_writelane_b32 v236, s2, 50
	s_addc_u32 s47, s1, 0
	v_cndmask_b32_e32 v0, v187, v2, vcc
	v_writelane_b32 v236, s3, 51
	s_lshl_b64 s[2:3], s[96:97], 2
	s_add_u32 s2, s0, s2
	s_addc_u32 s3, s1, s3
	s_add_u32 s8, s2, 0x1b000
	s_addc_u32 s9, s3, 0
	s_lshl_b64 s[2:3], s[16:17], 2
	s_add_u32 s10, s10, s2
	s_addc_u32 s11, s11, s3
	v_readlane_b32 s26, v237, 18
	v_readlane_b32 s27, v237, 19
	v_fmamk_f32 v0, v0, 0x3f19999a, v177
	s_add_u32 s12, s0, 0x20000
	s_mov_b32 s26, 0
	s_mul_i32 s27, s96, 12
	v_add_f32_e32 v192, 1.0, v0
	s_addc_u32 s13, s1, 0
	s_mov_b32 s49, -1
	v_writelane_b32 v236, 0, 62
	s_mov_b32 s2, s33
	v_readlane_b32 s22, v237, 14
	v_readlane_b32 s23, v237, 15
	v_readlane_b32 s24, v237, 16
	v_readlane_b32 s25, v237, 17
	s_branch .LBB0_196

; DI void band_item(const Params& P, char* lds_blk, int layer, int bp) {
;     ...
;     const int type = bp / 768, rem = bp % 768; const int bl = rem / 384, head = 2 * ((rem % 384) / 64) + half, blk = rem % 64;
; DI void phase_att(const Params& P, char* lds, int hb, int layer) {
;     ...
;         while (true) {
;             if (tid == 0) *slot = (int)atomicAdd(&ctr[qx], 1u);
;             __syncthreads();
;             const int qi = *slot;
;             __syncthreads();
;             if (qi >= NQ) break;
;             if (qi < 64) diff_item(P, lds, layer, qx, 63 - qi, tab_head);
;             else band_item(P, lds, layer, qx * 384 + (qi - 64));
.LBB0_199:
	v_readlane_b32 s25, v236, 62
	s_and_saveexec_b64 s[0:1], s[36:37]
	s_cbranch_execz .LBB0_201
	v_mov_b64_e32 v[2:3], s[56:57]
	flat_atomic_add v0, v[2:3], v176 sc0
	v_mov_b32_e32 v2, s53
	v_add_u32_e32 v2, s25, v2
	s_waitcnt vmcnt(0) lgkmcnt(0)
	ds_write_b32 v2, v0
.LBB0_201:
	s_or_b64 exec, exec, s[0:1]
	v_mov_b32_e32 v0, s53
	v_add_u32_e32 v0, s25, v0
	s_xor_b32 s25, s25, 4
	s_waitcnt lgkmcnt(0)
	s_barrier
	ds_read_b32 v0, v0
	v_writelane_b32 v236, s25, 62
	s_movk_i32 s0, 0x1bf
	s_waitcnt lgkmcnt(0)
	v_cmp_lt_i32_e64 s[38:39], s0, v0
	v_readfirstlane_b32 s25, v0
	s_and_b64 vcc, exec, s[38:39]
	s_cbranch_vccnz .LBB0_198
	s_cmp_gt_i32 s25, 63
	s_mov_b64 s[0:1], -1
	s_cbranch_scc0 .LBB0_243
	s_add_i32 s63, s54, s25
	s_and_b32 s0, s63, 0xffff
	s_mul_i32 s0, s0, 0xaaab
	s_lshr_b32 s50, s0, 25
	s_mul_i32 s0, s50, 0x300
	s_sub_i32 s0, s63, s0
	s_and_b32 s16, s0, 0xffff
	s_add_i32 s0, s16, 0x80
	s_cmpk_lt_u32 s16, 0x180
	s_cselect_b32 s0, s16, s0
	s_lshr_b32 s0, s0, 5
	v_mov_b32_e32 v10, v174
	s_and_b32 s0, s0, 14
	s_cmpk_lt_u32 s63, 0x300
	v_ashrrev_i32_e32 v0, 8, v10
	v_add_u32_e32 v108, s0, v0
	s_cselect_b64 s[0:1], -1, 0
	s_cmpk_gt_u32 s63, 0x2ff
	s_cselect_b64 s[40:41], -1, 0
	v_lshlrev_b32_e32 v106, 6, v108
	s_mov_b64 s[22:23], -1
	s_and_b64 vcc, exec, s[40:41]
	s_cbranch_vccz .LBB0_205
	v_add_u32_e32 v2, 0x480, v106
	v_add_u32_e32 v4, 0x780, v106
	v_add_u32_e32 v6, 0xa80, v106
	s_mov_b64 s[22:23], 0
